# RG-LRU folded into the four producer waves (segment aggregate in blocks 0-31, carry via LDS, redo with carry in blocks 32-63); no separate pre-pass
# speedup vs baseline: 1.0274x; 1.0042x over previous
.LBB0_872:
	s_cmp_lt_u32 s33, 4
	s_cbranch_scc1 .Lrg_init_done
	s_lshr_b32 s4, s91, 3
	s_and_b32 s5, s91, 7
	s_lshl_b32 s4, s4, 21
	s_lshl_b32 s5, s5, 7
	s_or_b32 s4, s4, s5
	s_lshl_b32 s5, s3, 19
	s_or_b32 s4, s4, s5
	v_lshl_add_u32 v172, v32, 1, s4
	v_mov_b32_e32 v167, v172
	v_mov_b32_e32 v168, v172
	v_mov_b32_e32 v164, 0
	v_mov_b32_e32 v165, 1.0
	v_mov_b32_e32 v166, 0
	v_mov_b32_e32 v169, 0
	v_mov_b32_e32 v170, 0xbdd2d3e8
	v_mov_b32_e32 v171, 0xc0135761
	v_add_u32_e32 v244, 0x1000, v167
	v_add_u32_e32 v245, 0x2000, v167
	v_add_u32_e32 v246, 0x3000, v167
	global_load_ushort v176, v167, s[10:11] offset:0
	global_load_ushort v192, v167, s[12:13] offset:0
	global_load_ushort v177, v167, s[10:11] offset:1024
	global_load_ushort v193, v167, s[12:13] offset:1024
	global_load_ushort v178, v167, s[10:11] offset:2048
	global_load_ushort v194, v167, s[12:13] offset:2048
	global_load_ushort v179, v167, s[10:11] offset:3072
	global_load_ushort v195, v167, s[12:13] offset:3072
	global_load_ushort v180, v244, s[10:11] offset:0
	global_load_ushort v196, v244, s[12:13] offset:0
	global_load_ushort v181, v244, s[10:11] offset:1024
	global_load_ushort v197, v244, s[12:13] offset:1024
	global_load_ushort v182, v244, s[10:11] offset:2048
	global_load_ushort v198, v244, s[12:13] offset:2048
	global_load_ushort v183, v244, s[10:11] offset:3072
	global_load_ushort v199, v244, s[12:13] offset:3072
	global_load_ushort v184, v245, s[10:11] offset:0
	global_load_ushort v200, v245, s[12:13] offset:0
	global_load_ushort v185, v245, s[10:11] offset:1024
	global_load_ushort v201, v245, s[12:13] offset:1024
	global_load_ushort v186, v245, s[10:11] offset:2048
	global_load_ushort v202, v245, s[12:13] offset:2048
	global_load_ushort v187, v245, s[10:11] offset:3072
	global_load_ushort v203, v245, s[12:13] offset:3072
	global_load_ushort v188, v246, s[10:11] offset:0
	global_load_ushort v204, v246, s[12:13] offset:0
	global_load_ushort v189, v246, s[10:11] offset:1024
	global_load_ushort v205, v246, s[12:13] offset:1024
	global_load_ushort v190, v246, s[10:11] offset:2048
	global_load_ushort v206, v246, s[12:13] offset:2048
	global_load_ushort v191, v246, s[10:11] offset:3072
	global_load_ushort v207, v246, s[12:13] offset:3072
	v_add_u32_e32 v167, 0x4000, v167

.LBB0_912:
	s_cmp_gt_u32 s20, 61
	s_cbranch_scc1 .Lrg_w0
	s_waitcnt vmcnt(63)
	s_branch .Lrg_w1

.Lrg_w1:
	s_cmp_lt_u32 s20, 32
	s_cbranch_scc0 .Lrg_pass2
	v_lshlrev_b32_e32 v224, 16, v176
	v_mul_f32_e32 v224, 0x3fb8aa3b, v224
	v_lshlrev_b32_e32 v225, 16, v177
	v_mul_f32_e32 v225, 0x3fb8aa3b, v225
	v_lshlrev_b32_e32 v226, 16, v178
	v_mul_f32_e32 v226, 0x3fb8aa3b, v226
	v_lshlrev_b32_e32 v227, 16, v179
	v_mul_f32_e32 v227, 0x3fb8aa3b, v227
	v_exp_f32_e32 v224, v224
	v_lshlrev_b32_e32 v228, 16, v192
	v_exp_f32_e32 v225, v225
	v_lshlrev_b32_e32 v229, 16, v193
	v_exp_f32_e32 v226, v226
	v_lshlrev_b32_e32 v230, 16, v194
	v_exp_f32_e32 v227, v227
	v_lshlrev_b32_e32 v231, 16, v195
	v_fma_f32 v164, v224, v164, v228
	v_mul_f32_e32 v165, v165, v224
	v_fma_f32 v164, v225, v164, v229
	v_mul_f32_e32 v165, v165, v225
	v_fma_f32 v164, v226, v164, v230
	v_mul_f32_e32 v165, v165, v226
	v_fma_f32 v164, v227, v164, v231
	v_mul_f32_e32 v165, v165, v227
	v_lshlrev_b32_e32 v224, 16, v180
	v_mul_f32_e32 v224, 0x3fb8aa3b, v224
	v_lshlrev_b32_e32 v225, 16, v181
	v_mul_f32_e32 v225, 0x3fb8aa3b, v225
	v_lshlrev_b32_e32 v226, 16, v182
	v_mul_f32_e32 v226, 0x3fb8aa3b, v226
	v_lshlrev_b32_e32 v227, 16, v183
	v_mul_f32_e32 v227, 0x3fb8aa3b, v227
	v_exp_f32_e32 v224, v224
	v_lshlrev_b32_e32 v228, 16, v196
	v_exp_f32_e32 v225, v225
	v_lshlrev_b32_e32 v229, 16, v197
	v_exp_f32_e32 v226, v226
	v_lshlrev_b32_e32 v230, 16, v198
	v_exp_f32_e32 v227, v227
	v_lshlrev_b32_e32 v231, 16, v199
	v_fma_f32 v164, v224, v164, v228
	v_mul_f32_e32 v165, v165, v224
	v_fma_f32 v164, v225, v164, v229
	v_mul_f32_e32 v165, v165, v225
	v_fma_f32 v164, v226, v164, v230
	v_mul_f32_e32 v165, v165, v226
	v_fma_f32 v164, v227, v164, v231
	v_mul_f32_e32 v165, v165, v227
	v_lshlrev_b32_e32 v224, 16, v184
	v_mul_f32_e32 v224, 0x3fb8aa3b, v224
	v_lshlrev_b32_e32 v225, 16, v185
	v_mul_f32_e32 v225, 0x3fb8aa3b, v225
	v_lshlrev_b32_e32 v226, 16, v186
	v_mul_f32_e32 v226, 0x3fb8aa3b, v226
	v_lshlrev_b32_e32 v227, 16, v187
	v_mul_f32_e32 v227, 0x3fb8aa3b, v227
	v_exp_f32_e32 v224, v224
	v_lshlrev_b32_e32 v228, 16, v200
	v_exp_f32_e32 v225, v225
	v_lshlrev_b32_e32 v229, 16, v201
	v_exp_f32_e32 v226, v226
	v_lshlrev_b32_e32 v230, 16, v202
	v_exp_f32_e32 v227, v227
	v_lshlrev_b32_e32 v231, 16, v203
	v_fma_f32 v164, v224, v164, v228
	v_mul_f32_e32 v165, v165, v224
	v_fma_f32 v164, v225, v164, v229
	v_mul_f32_e32 v165, v165, v225
	v_fma_f32 v164, v226, v164, v230
	v_mul_f32_e32 v165, v165, v226
	v_fma_f32 v164, v227, v164, v231
	v_mul_f32_e32 v165, v165, v227
	v_lshlrev_b32_e32 v224, 16, v188
	v_mul_f32_e32 v224, 0x3fb8aa3b, v224
	v_lshlrev_b32_e32 v225, 16, v189
	v_mul_f32_e32 v225, 0x3fb8aa3b, v225
	v_lshlrev_b32_e32 v226, 16, v190
	v_mul_f32_e32 v226, 0x3fb8aa3b, v226
	v_lshlrev_b32_e32 v227, 16, v191
	v_mul_f32_e32 v227, 0x3fb8aa3b, v227
	v_exp_f32_e32 v224, v224
	v_lshlrev_b32_e32 v228, 16, v204
	v_exp_f32_e32 v225, v225
	v_lshlrev_b32_e32 v229, 16, v205
	v_exp_f32_e32 v226, v226
	v_lshlrev_b32_e32 v230, 16, v206
	v_exp_f32_e32 v227, v227
	v_lshlrev_b32_e32 v231, 16, v207
	v_fma_f32 v164, v224, v164, v228
	v_mul_f32_e32 v165, v165, v224
	v_fma_f32 v164, v225, v164, v229
	v_mul_f32_e32 v165, v165, v225
	v_fma_f32 v164, v226, v164, v230
	v_mul_f32_e32 v165, v165, v226
	v_fma_f32 v164, v227, v164, v231
	v_mul_f32_e32 v165, v165, v227
	s_cmp_eq_u32 s20, 31
	s_cbranch_scc0 .Lrg_issue
	v_lshlrev_b32_e32 v224, 2, v32
	s_lshl_b32 s4, s3, 8
	v_add_u32_e32 v224, s4, v224
	v_add_u32_e32 v224, 0x19000, v224
	ds_write_b32 v224, v165
	ds_write_b32 v224, v164 offset:1024
	v_mov_b32_e32 v167, v172
	s_branch .Lrg_issue
.Lrg_pass2:
	s_cmp_eq_u32 s20, 32
	s_cbranch_scc0 .Lrg_p2go
	s_cmp_eq_u32 s3, 0
	s_cbranch_scc1 .Lrg_p2go
	v_lshlrev_b32_e32 v224, 2, v32
	v_add_u32_e32 v224, 0x19000, v224
	s_mov_b32 s4, 0
.Lrg_c:
	ds_read_b32 v228, v224
	ds_read_b32 v229, v224 offset:1024
	v_add_u32_e32 v224, 0x100, v224
	s_add_i32 s4, s4, 1
	s_cmp_lt_u32 s4, s3
	s_waitcnt lgkmcnt(0)
	v_fma_f32 v166, v228, v166, v229
	s_cbranch_scc1 .Lrg_c
.Lrg_p2go:
	v_add_u32_e32 v244, 0x1000, v168
	v_add_u32_e32 v245, 0x2000, v168
	v_add_u32_e32 v246, 0x3000, v168
	v_lshlrev_b32_e32 v224, 16, v176
	v_mul_f32_e32 v224, 0x3fb8aa3b, v224
	v_lshlrev_b32_e32 v225, 16, v177
	v_mul_f32_e32 v225, 0x3fb8aa3b, v225
	v_lshlrev_b32_e32 v226, 16, v178
	v_mul_f32_e32 v226, 0x3fb8aa3b, v226
	v_lshlrev_b32_e32 v227, 16, v179
	v_mul_f32_e32 v227, 0x3fb8aa3b, v227
	v_exp_f32_e32 v224, v224
	v_lshlrev_b32_e32 v228, 16, v192
	v_exp_f32_e32 v225, v225
	v_lshlrev_b32_e32 v229, 16, v193
	v_exp_f32_e32 v226, v226
	v_lshlrev_b32_e32 v230, 16, v194
	v_exp_f32_e32 v227, v227
	v_lshlrev_b32_e32 v231, 16, v195
	v_lshlrev_b32_e32 v232, 16, v208
	v_mul_f32_e32 v236, v232, v232
	v_lshlrev_b32_e32 v233, 16, v209
	v_mul_f32_e32 v237, v233, v233
	v_lshlrev_b32_e32 v234, 16, v210
	v_mul_f32_e32 v238, v234, v234
	v_lshlrev_b32_e32 v235, 16, v211
	v_mul_f32_e32 v239, v235, v235
	v_fma_f32 v236, v236, v170, v171
	v_fma_f32 v166, v224, v166, v228
	v_mul_f32_e32 v240, v166, v232
	v_fma_f32 v237, v237, v170, v171
	v_fma_f32 v166, v225, v166, v229
	v_mul_f32_e32 v241, v166, v233
	v_fma_f32 v238, v238, v170, v171
	v_fma_f32 v166, v226, v166, v230
	v_mul_f32_e32 v242, v166, v234
	v_fma_f32 v239, v239, v170, v171
	v_fma_f32 v166, v227, v166, v231
	v_mul_f32_e32 v243, v166, v235
	v_mul_f32_e32 v236, v236, v232
	v_mul_f32_e32 v237, v237, v233
	v_mul_f32_e32 v238, v238, v234
	v_mul_f32_e32 v239, v239, v235
	v_exp_f32_e32 v236, v236
	v_exp_f32_e32 v237, v237
	v_exp_f32_e32 v238, v238
	v_exp_f32_e32 v239, v239
	s_nop 0
	v_add_f32_e32 v236, 1.0, v236
	v_add_f32_e32 v237, 1.0, v237
	v_add_f32_e32 v238, 1.0, v238
	v_add_f32_e32 v239, 1.0, v239
	v_rcp_f32_e32 v236, v236
	v_rcp_f32_e32 v237, v237
	v_rcp_f32_e32 v238, v238
	v_rcp_f32_e32 v239, v239
	s_nop 0
	v_mul_f32_e32 v240, v240, v236
	v_mul_f32_e32 v241, v241, v237
	v_mul_f32_e32 v242, v242, v238
	v_mul_f32_e32 v243, v243, v239
	v_cvt_pk_bf16_f32 v240, v240, v169
	v_cvt_pk_bf16_f32 v241, v241, v169
	v_cvt_pk_bf16_f32 v242, v242, v169
	v_cvt_pk_bf16_f32 v243, v243, v169
	global_store_short v168, v240, s[16:17] offset:0
	global_store_short v168, v241, s[16:17] offset:1024
	global_store_short v168, v242, s[16:17] offset:2048
	global_store_short v168, v243, s[16:17] offset:3072
	v_lshlrev_b32_e32 v224, 16, v180
	v_mul_f32_e32 v224, 0x3fb8aa3b, v224
	v_lshlrev_b32_e32 v225, 16, v181
	v_mul_f32_e32 v225, 0x3fb8aa3b, v225
	v_lshlrev_b32_e32 v226, 16, v182
	v_mul_f32_e32 v226, 0x3fb8aa3b, v226
	v_lshlrev_b32_e32 v227, 16, v183
	v_mul_f32_e32 v227, 0x3fb8aa3b, v227
	v_exp_f32_e32 v224, v224
	v_lshlrev_b32_e32 v228, 16, v196
	v_exp_f32_e32 v225, v225
	v_lshlrev_b32_e32 v229, 16, v197
	v_exp_f32_e32 v226, v226
	v_lshlrev_b32_e32 v230, 16, v198
	v_exp_f32_e32 v227, v227
	v_lshlrev_b32_e32 v231, 16, v199
	v_lshlrev_b32_e32 v232, 16, v212
	v_mul_f32_e32 v236, v232, v232
	v_lshlrev_b32_e32 v233, 16, v213
	v_mul_f32_e32 v237, v233, v233
	v_lshlrev_b32_e32 v234, 16, v214
	v_mul_f32_e32 v238, v234, v234
	v_lshlrev_b32_e32 v235, 16, v215
	v_mul_f32_e32 v239, v235, v235
	v_fma_f32 v236, v236, v170, v171
	v_fma_f32 v166, v224, v166, v228
	v_mul_f32_e32 v240, v166, v232
	v_fma_f32 v237, v237, v170, v171
	v_fma_f32 v166, v225, v166, v229
	v_mul_f32_e32 v241, v166, v233
	v_fma_f32 v238, v238, v170, v171
	v_fma_f32 v166, v226, v166, v230
	v_mul_f32_e32 v242, v166, v234
	v_fma_f32 v239, v239, v170, v171
	v_fma_f32 v166, v227, v166, v231
	v_mul_f32_e32 v243, v166, v235
	v_mul_f32_e32 v236, v236, v232
	v_mul_f32_e32 v237, v237, v233
	v_mul_f32_e32 v238, v238, v234
	v_mul_f32_e32 v239, v239, v235
	v_exp_f32_e32 v236, v236
	v_exp_f32_e32 v237, v237
	v_exp_f32_e32 v238, v238
	v_exp_f32_e32 v239, v239
	s_nop 0
	v_add_f32_e32 v236, 1.0, v236
	v_add_f32_e32 v237, 1.0, v237
	v_add_f32_e32 v238, 1.0, v238
	v_add_f32_e32 v239, 1.0, v239
	v_rcp_f32_e32 v236, v236
	v_rcp_f32_e32 v237, v237
	v_rcp_f32_e32 v238, v238
	v_rcp_f32_e32 v239, v239
	s_nop 0
	v_mul_f32_e32 v240, v240, v236
	v_mul_f32_e32 v241, v241, v237
	v_mul_f32_e32 v242, v242, v238
	v_mul_f32_e32 v243, v243, v239
	v_cvt_pk_bf16_f32 v240, v240, v169
	v_cvt_pk_bf16_f32 v241, v241, v169
	v_cvt_pk_bf16_f32 v242, v242, v169
	v_cvt_pk_bf16_f32 v243, v243, v169
	global_store_short v244, v240, s[16:17] offset:0
	global_store_short v244, v241, s[16:17] offset:1024
	global_store_short v244, v242, s[16:17] offset:2048
	global_store_short v244, v243, s[16:17] offset:3072
	v_lshlrev_b32_e32 v224, 16, v184
	v_mul_f32_e32 v224, 0x3fb8aa3b, v224
	v_lshlrev_b32_e32 v225, 16, v185
	v_mul_f32_e32 v225, 0x3fb8aa3b, v225
	v_lshlrev_b32_e32 v226, 16, v186
	v_mul_f32_e32 v226, 0x3fb8aa3b, v226
	v_lshlrev_b32_e32 v227, 16, v187
	v_mul_f32_e32 v227, 0x3fb8aa3b, v227
	v_exp_f32_e32 v224, v224
	v_lshlrev_b32_e32 v228, 16, v200
	v_exp_f32_e32 v225, v225
	v_lshlrev_b32_e32 v229, 16, v201
	v_exp_f32_e32 v226, v226
	v_lshlrev_b32_e32 v230, 16, v202
	v_exp_f32_e32 v227, v227
	v_lshlrev_b32_e32 v231, 16, v203
	v_lshlrev_b32_e32 v232, 16, v216
	v_mul_f32_e32 v236, v232, v232
	v_lshlrev_b32_e32 v233, 16, v217
	v_mul_f32_e32 v237, v233, v233
	v_lshlrev_b32_e32 v234, 16, v218
	v_mul_f32_e32 v238, v234, v234
	v_lshlrev_b32_e32 v235, 16, v219
	v_mul_f32_e32 v239, v235, v235
	v_fma_f32 v236, v236, v170, v171
	v_fma_f32 v166, v224, v166, v228
	v_mul_f32_e32 v240, v166, v232
	v_fma_f32 v237, v237, v170, v171
	v_fma_f32 v166, v225, v166, v229
	v_mul_f32_e32 v241, v166, v233
	v_fma_f32 v238, v238, v170, v171
	v_fma_f32 v166, v226, v166, v230
	v_mul_f32_e32 v242, v166, v234
	v_fma_f32 v239, v239, v170, v171
	v_fma_f32 v166, v227, v166, v231
	v_mul_f32_e32 v243, v166, v235
	v_mul_f32_e32 v236, v236, v232
	v_mul_f32_e32 v237, v237, v233
	v_mul_f32_e32 v238, v238, v234
	v_mul_f32_e32 v239, v239, v235
	v_exp_f32_e32 v236, v236
	v_exp_f32_e32 v237, v237
	v_exp_f32_e32 v238, v238
	v_exp_f32_e32 v239, v239
	s_nop 0
	v_add_f32_e32 v236, 1.0, v236
	v_add_f32_e32 v237, 1.0, v237
	v_add_f32_e32 v238, 1.0, v238
	v_add_f32_e32 v239, 1.0, v239
	v_rcp_f32_e32 v236, v236
	v_rcp_f32_e32 v237, v237
	v_rcp_f32_e32 v238, v238
	v_rcp_f32_e32 v239, v239
	s_nop 0
	v_mul_f32_e32 v240, v240, v236
	v_mul_f32_e32 v241, v241, v237
	v_mul_f32_e32 v242, v242, v238
	v_mul_f32_e32 v243, v243, v239
	v_cvt_pk_bf16_f32 v240, v240, v169
	v_cvt_pk_bf16_f32 v241, v241, v169
	v_cvt_pk_bf16_f32 v242, v242, v169
	v_cvt_pk_bf16_f32 v243, v243, v169
	global_store_short v245, v240, s[16:17] offset:0
	global_store_short v245, v241, s[16:17] offset:1024
	global_store_short v245, v242, s[16:17] offset:2048
	global_store_short v245, v243, s[16:17] offset:3072
	v_lshlrev_b32_e32 v224, 16, v188
	v_mul_f32_e32 v224, 0x3fb8aa3b, v224
	v_lshlrev_b32_e32 v225, 16, v189
	v_mul_f32_e32 v225, 0x3fb8aa3b, v225
	v_lshlrev_b32_e32 v226, 16, v190
	v_mul_f32_e32 v226, 0x3fb8aa3b, v226
	v_lshlrev_b32_e32 v227, 16, v191
	v_mul_f32_e32 v227, 0x3fb8aa3b, v227
	v_exp_f32_e32 v224, v224
	v_lshlrev_b32_e32 v228, 16, v204
	v_exp_f32_e32 v225, v225
	v_lshlrev_b32_e32 v229, 16, v205
	v_exp_f32_e32 v226, v226
	v_lshlrev_b32_e32 v230, 16, v206
	v_exp_f32_e32 v227, v227
	v_lshlrev_b32_e32 v231, 16, v207
	v_lshlrev_b32_e32 v232, 16, v220
	v_mul_f32_e32 v236, v232, v232
	v_lshlrev_b32_e32 v233, 16, v221
	v_mul_f32_e32 v237, v233, v233
	v_lshlrev_b32_e32 v234, 16, v222
	v_mul_f32_e32 v238, v234, v234
	v_lshlrev_b32_e32 v235, 16, v223
	v_mul_f32_e32 v239, v235, v235
	v_fma_f32 v236, v236, v170, v171
	v_fma_f32 v166, v224, v166, v228
	v_mul_f32_e32 v240, v166, v232
	v_fma_f32 v237, v237, v170, v171
	v_fma_f32 v166, v225, v166, v229
	v_mul_f32_e32 v241, v166, v233
	v_fma_f32 v238, v238, v170, v171
	v_fma_f32 v166, v226, v166, v230
	v_mul_f32_e32 v242, v166, v234
	v_fma_f32 v239, v239, v170, v171
	v_fma_f32 v166, v227, v166, v231
	v_mul_f32_e32 v243, v166, v235
	v_mul_f32_e32 v236, v236, v232
	v_mul_f32_e32 v237, v237, v233
	v_mul_f32_e32 v238, v238, v234
	v_mul_f32_e32 v239, v239, v235
	v_exp_f32_e32 v236, v236
	v_exp_f32_e32 v237, v237
	v_exp_f32_e32 v238, v238
	v_exp_f32_e32 v239, v239
	s_nop 0
	v_add_f32_e32 v236, 1.0, v236
	v_add_f32_e32 v237, 1.0, v237
	v_add_f32_e32 v238, 1.0, v238
	v_add_f32_e32 v239, 1.0, v239
	v_rcp_f32_e32 v236, v236
	v_rcp_f32_e32 v237, v237
	v_rcp_f32_e32 v238, v238
	v_rcp_f32_e32 v239, v239
	s_nop 0
	v_mul_f32_e32 v240, v240, v236
	v_mul_f32_e32 v241, v241, v237
	v_mul_f32_e32 v242, v242, v238
	v_mul_f32_e32 v243, v243, v239
	v_cvt_pk_bf16_f32 v240, v240, v169
	v_cvt_pk_bf16_f32 v241, v241, v169
	v_cvt_pk_bf16_f32 v242, v242, v169
	v_cvt_pk_bf16_f32 v243, v243, v169
	global_store_short v246, v240, s[16:17] offset:0
	global_store_short v246, v241, s[16:17] offset:1024
	global_store_short v246, v242, s[16:17] offset:2048
	global_store_short v246, v243, s[16:17] offset:3072
	v_add_u32_e32 v168, 0x4000, v168
.Lrg_issue:
	s_cmp_eq_u32 s20, 63
	s_cbranch_scc1 .LBB0_892
	s_cmp_lt_u32 s20, 31
	s_cbranch_scc0 .Lrg_issue2
	v_add_u32_e32 v244, 0x1000, v167
	v_add_u32_e32 v245, 0x2000, v167
	v_add_u32_e32 v246, 0x3000, v167
	global_load_ushort v176, v167, s[10:11] offset:0
	global_load_ushort v192, v167, s[12:13] offset:0
	global_load_ushort v177, v167, s[10:11] offset:1024
	global_load_ushort v193, v167, s[12:13] offset:1024
	global_load_ushort v178, v167, s[10:11] offset:2048
	global_load_ushort v194, v167, s[12:13] offset:2048
	global_load_ushort v179, v167, s[10:11] offset:3072
	global_load_ushort v195, v167, s[12:13] offset:3072
	global_load_ushort v180, v244, s[10:11] offset:0
	global_load_ushort v196, v244, s[12:13] offset:0
	global_load_ushort v181, v244, s[10:11] offset:1024
	global_load_ushort v197, v244, s[12:13] offset:1024
	global_load_ushort v182, v244, s[10:11] offset:2048
	global_load_ushort v198, v244, s[12:13] offset:2048
	global_load_ushort v183, v244, s[10:11] offset:3072
	global_load_ushort v199, v244, s[12:13] offset:3072
	global_load_ushort v184, v245, s[10:11] offset:0
	global_load_ushort v200, v245, s[12:13] offset:0
	global_load_ushort v185, v245, s[10:11] offset:1024
	global_load_ushort v201, v245, s[12:13] offset:1024
	global_load_ushort v186, v245, s[10:11] offset:2048
	global_load_ushort v202, v245, s[12:13] offset:2048
	global_load_ushort v187, v245, s[10:11] offset:3072
	global_load_ushort v203, v245, s[12:13] offset:3072
	global_load_ushort v188, v246, s[10:11] offset:0
	global_load_ushort v204, v246, s[12:13] offset:0
	global_load_ushort v189, v246, s[10:11] offset:1024
	global_load_ushort v205, v246, s[12:13] offset:1024
	global_load_ushort v190, v246, s[10:11] offset:2048
	global_load_ushort v206, v246, s[12:13] offset:2048
	global_load_ushort v191, v246, s[10:11] offset:3072
	global_load_ushort v207, v246, s[12:13] offset:3072
	v_add_u32_e32 v167, 0x4000, v167
	s_branch .LBB0_892
.Lrg_issue2:
	v_add_u32_e32 v244, 0x1000, v167
	v_add_u32_e32 v245, 0x2000, v167
	v_add_u32_e32 v246, 0x3000, v167
	global_load_ushort v176, v167, s[10:11] offset:0
	global_load_ushort v192, v167, s[12:13] offset:0
	global_load_ushort v208, v167, s[14:15] offset:0
	global_load_ushort v177, v167, s[10:11] offset:1024
	global_load_ushort v193, v167, s[12:13] offset:1024
	global_load_ushort v209, v167, s[14:15] offset:1024
	global_load_ushort v178, v167, s[10:11] offset:2048
	global_load_ushort v194, v167, s[12:13] offset:2048
	global_load_ushort v210, v167, s[14:15] offset:2048
	global_load_ushort v179, v167, s[10:11] offset:3072
	global_load_ushort v195, v167, s[12:13] offset:3072
	global_load_ushort v211, v167, s[14:15] offset:3072
	global_load_ushort v180, v244, s[10:11] offset:0
	global_load_ushort v196, v244, s[12:13] offset:0
	global_load_ushort v212, v244, s[14:15] offset:0
	global_load_ushort v181, v244, s[10:11] offset:1024
	global_load_ushort v197, v244, s[12:13] offset:1024
	global_load_ushort v213, v244, s[14:15] offset:1024
	global_load_ushort v182, v244, s[10:11] offset:2048
	global_load_ushort v198, v244, s[12:13] offset:2048
	global_load_ushort v214, v244, s[14:15] offset:2048
	global_load_ushort v183, v244, s[10:11] offset:3072
	global_load_ushort v199, v244, s[12:13] offset:3072
	global_load_ushort v215, v244, s[14:15] offset:3072
	global_load_ushort v184, v245, s[10:11] offset:0
	global_load_ushort v200, v245, s[12:13] offset:0
	global_load_ushort v216, v245, s[14:15] offset:0
	global_load_ushort v185, v245, s[10:11] offset:1024
	global_load_ushort v201, v245, s[12:13] offset:1024
	global_load_ushort v217, v245, s[14:15] offset:1024
	global_load_ushort v186, v245, s[10:11] offset:2048
	global_load_ushort v202, v245, s[12:13] offset:2048
	global_load_ushort v218, v245, s[14:15] offset:2048
	global_load_ushort v187, v245, s[10:11] offset:3072
	global_load_ushort v203, v245, s[12:13] offset:3072
	global_load_ushort v219, v245, s[14:15] offset:3072
	global_load_ushort v188, v246, s[10:11] offset:0
	global_load_ushort v204, v246, s[12:13] offset:0
	global_load_ushort v220, v246, s[14:15] offset:0
	global_load_ushort v189, v246, s[10:11] offset:1024
	global_load_ushort v205, v246, s[12:13] offset:1024
	global_load_ushort v221, v246, s[14:15] offset:1024
	global_load_ushort v190, v246, s[10:11] offset:2048
	global_load_ushort v206, v246, s[12:13] offset:2048
	global_load_ushort v222, v246, s[14:15] offset:2048
	global_load_ushort v191, v246, s[10:11] offset:3072
	global_load_ushort v207, v246, s[12:13] offset:3072
	global_load_ushort v223, v246, s[14:15] offset:3072
	v_add_u32_e32 v167, 0x4000, v167
	s_branch .LBB0_892

.LBB0_916:
	s_and_b64 vcc, exec, s[4:5]
	s_cbranch_vccz .LBB0_871
	s_and_b32 s4, s83, 0xfffff800
	s_ashr_i32 s5, s4, 31
	s_and_b32 s6, s90, 7
	s_lshl_b64 s[4:5], s[4:5], 10
	s_lshl_b32 s6, s6, 7
	s_waitcnt lgkmcnt(0)
	s_barrier
	s_or_b32 s4, s4, s6
	v_lshl_add_u64 v[0:1], v[40:41], 0, s[4:5]
	v_mov_b32_e32 v4, 0
	s_mov_b32 s6, 0
	v_mov_b32_e32 v5, 0
	v_mov_b32_e32 v6, 0
	v_mov_b32_e32 v7, 0
	v_mov_b32_e32 v8, 0
	v_mov_b32_e32 v9, 0
	v_mov_b32_e32 v10, 0
	v_mov_b32_e32 v11, 0
	s_waitcnt vmcnt(0)
	v_mov_b32_e32 v12, 0
	v_mov_b32_e32 v13, 0
	v_mov_b32_e32 v14, 0
	v_mov_b32_e32 v15, 0
	v_mov_b32_e32 v16, 0
	v_mov_b32_e32 v17, 0
	v_mov_b32_e32 v18, 0
	v_mov_b32_e32 v19, 0
	s_add_u32 s4, s4, s96
	s_addc_u32 s5, s5, s97
	s_add_u32 s4, s4, 0x1d800000
	s_addc_u32 s5, s5, 0
	v_add_u32_e32 v52, 0xfffffb00, v38
	v_lshrrev_b32_e32 v52, 1, v52
	v_lshrrev_b32_e32 v53, 4, v32
	v_and_b32_e32 v54, 1, v53
	v_lshrrev_b32_e32 v53, 1, v53
	v_lshl_or_b32 v53, v54, 1, v53
	v_lshl_add_u32 v52, v53, 10, v52
	v_lshrrev_b32_e32 v55, 4, v32
	v_lshlrev_b32_e32 v55, 6, v55
	v_and_b32_e32 v68, 15, v32
	v_lshrrev_b32_e32 v69, 2, v68
	v_and_b32_e32 v68, 3, v68
	v_lshlrev_b32_e32 v69, 6, v69
	v_lshl_or_b32 v69, v68, 2, v69
	v_lshrrev_b32_e32 v68, 4, v32
	v_lshl_or_b32 v69, v68, 4, v69
	s_setprio 2
